# v31 + bf16 GEMM epilogue stores issued as global (not flat): no lgkmcnt coupling with the next tile's LDS waits
# speedup vs baseline: 1.0045x; 1.0007x over previous
; __device__ __forceinline__ unsigned cvt_pk_bf16(float lo, float hi) { unsigned r; asm volatile("v_cvt_pk_bf16_f32 %0, %1, %2" : "=v"(r) : "v"(lo), "v"(hi)); return r; }
;     __device__ __forceinline__ void operator()(const pg8::f32x4 (&acc)[2][2][4][2], const pg8::Unit& u, int wr, int wc, int fr, int fq) const {
;         const int row0 = NMETA + u.pm * 256 + wr * 64 + fr, col0 = u.pn * 256 + wc * 32 + 8 * fq;
; #pragma unroll
;         for (int ai = 0; ai < 2; ++ai)
; #pragma unroll
;             for (int m = 0; m < 4; ++m) { bf16_t* rowp = O + (size_t)(row0 + ai * 128 + m * 16) * PW + col0;
; #pragma unroll
;                 for (int bj = 0; bj < 2; ++bj) { const pg8::f32x4 v0 = acc[ai][bj][m][0], v1 = acc[ai][bj][m][1];
;                     u32x4 w; w.x = cvt_pk_bf16(v0[0], v0[1]); w.y = cvt_pk_bf16(v0[2], v0[3]); w.z = cvt_pk_bf16(v1[0], v1[1]); w.w = cvt_pk_bf16(v1[2], v1[3]);
;                     *(u32x4*)(rowp + bj * 128) = w; } }
.LBB0_219:
	v_lshl_or_b32 v148, s52, 8, v150
	v_lshl_add_u32 v158, s26, 8, v1
	v_ashrrev_i32_e32 v149, 31, v148
	v_mov_b64_e32 v[146:147], s[10:11]
	v_mad_i64_i32 v[156:157], s[28:29], v158, s49, v[146:147]
	v_lshlrev_b64 v[148:149], 1, v[148:149]
	v_lshl_add_u64 v[156:157], v[156:157], 0, v[148:149]
	v_cvt_pk_bf16_f32 v126, v126, v127
	v_cvt_pk_bf16_f32 v127, v128, v129
	v_cvt_pk_bf16_f32 v128, v122, v123
	v_cvt_pk_bf16_f32 v129, v124, v125
	global_store_dwordx4 v[156:157], v[126:129], off
	v_cvt_pk_bf16_f32 v114, v114, v115
	v_cvt_pk_bf16_f32 v115, v116, v117
	v_cvt_pk_bf16_f32 v116, v106, v107
	v_add_u32_e32 v106, 16, v158
	v_mad_i64_i32 v[106:107], s[28:29], v106, s49, v[146:147]
	v_cvt_pk_bf16_f32 v117, v108, v109
	global_store_dwordx4 v[156:157], v[114:117], off offset:256
	s_andn2_b64 vcc, exec, s[6:7]
	s_mov_b64 s[6:7], -1
	v_lshl_add_u64 v[114:115], v[106:107], 0, v[148:149]
	v_cvt_pk_bf16_f32 v106, v118, v119
	v_cvt_pk_bf16_f32 v107, v120, v121
	v_cvt_pk_bf16_f32 v108, v110, v111
	v_cvt_pk_bf16_f32 v109, v112, v113
	global_store_dwordx4 v[114:115], v[106:109], off
	v_cvt_pk_bf16_f32 v98, v98, v99
	v_cvt_pk_bf16_f32 v99, v100, v101
	v_cvt_pk_bf16_f32 v100, v90, v91
	v_or_b32_e32 v90, 32, v158
	v_mad_i64_i32 v[90:91], s[28:29], v90, s49, v[146:147]
	v_cvt_pk_bf16_f32 v101, v92, v93
	global_store_dwordx4 v[114:115], v[98:101], off offset:256
	s_nop 1
	v_lshl_add_u64 v[98:99], v[90:91], 0, v[148:149]
	v_cvt_pk_bf16_f32 v90, v102, v103
	v_cvt_pk_bf16_f32 v91, v104, v105
	v_cvt_pk_bf16_f32 v92, v94, v95
	v_cvt_pk_bf16_f32 v93, v96, v97
	global_store_dwordx4 v[98:99], v[90:93], off
	v_cvt_pk_bf16_f32 v82, v82, v83
	v_cvt_pk_bf16_f32 v83, v84, v85
	v_cvt_pk_bf16_f32 v84, v74, v75
	v_add_u32_e32 v74, 48, v158
	v_mad_i64_i32 v[74:75], s[28:29], v74, s49, v[146:147]
	v_cvt_pk_bf16_f32 v85, v76, v77
	global_store_dwordx4 v[98:99], v[82:85], off offset:256
	s_nop 1
	v_lshl_add_u64 v[82:83], v[74:75], 0, v[148:149]
	v_cvt_pk_bf16_f32 v74, v86, v87
	v_cvt_pk_bf16_f32 v75, v88, v89
	v_cvt_pk_bf16_f32 v76, v78, v79
	v_cvt_pk_bf16_f32 v77, v80, v81
	global_store_dwordx4 v[82:83], v[74:77], off
	v_cvt_pk_bf16_f32 v70, v70, v71
	v_cvt_pk_bf16_f32 v71, v72, v73
	v_cvt_pk_bf16_f32 v72, v66, v67
	v_add_u32_e32 v66, 0x80, v158
	v_mad_i64_i32 v[66:67], s[28:29], v66, s49, v[146:147]
	v_lshl_add_u64 v[66:67], v[66:67], 0, v[148:149]
	v_cvt_pk_bf16_f32 v73, v68, v69
	global_store_dwordx4 v[82:83], v[70:73], off offset:256
	v_cvt_pk_bf16_f32 v62, v62, v63
	v_cvt_pk_bf16_f32 v63, v64, v65
	v_cvt_pk_bf16_f32 v64, v58, v59
	v_cvt_pk_bf16_f32 v65, v60, v61
	global_store_dwordx4 v[66:67], v[62:65], off
	v_cvt_pk_bf16_f32 v50, v50, v51
	v_cvt_pk_bf16_f32 v51, v52, v53
	v_cvt_pk_bf16_f32 v52, v42, v43
	v_add_u32_e32 v42, 0x90, v158
	v_mad_i64_i32 v[42:43], s[28:29], v42, s49, v[146:147]
	v_cvt_pk_bf16_f32 v53, v44, v45
	global_store_dwordx4 v[66:67], v[50:53], off offset:256
	s_nop 1
	v_lshl_add_u64 v[50:51], v[42:43], 0, v[148:149]
	v_cvt_pk_bf16_f32 v42, v54, v55
	v_cvt_pk_bf16_f32 v43, v56, v57
	v_cvt_pk_bf16_f32 v44, v46, v47
	v_cvt_pk_bf16_f32 v45, v48, v49
	global_store_dwordx4 v[50:51], v[42:45], off
	v_cvt_pk_bf16_f32 v34, v34, v35
	v_cvt_pk_bf16_f32 v35, v36, v37
	v_cvt_pk_bf16_f32 v36, v26, v27
	v_add_u32_e32 v26, 0xa0, v158
	v_mad_i64_i32 v[26:27], s[28:29], v26, s49, v[146:147]
	v_cvt_pk_bf16_f32 v37, v28, v29
	global_store_dwordx4 v[50:51], v[34:37], off offset:256
	s_nop 1
	v_lshl_add_u64 v[34:35], v[26:27], 0, v[148:149]
	v_cvt_pk_bf16_f32 v26, v38, v39
	v_cvt_pk_bf16_f32 v27, v40, v41
	v_cvt_pk_bf16_f32 v28, v30, v31
	v_cvt_pk_bf16_f32 v29, v32, v33
	global_store_dwordx4 v[34:35], v[26:29], off
	v_cvt_pk_bf16_f32 v18, v18, v19
	v_cvt_pk_bf16_f32 v19, v20, v21
	v_cvt_pk_bf16_f32 v20, v10, v11
	v_add_u32_e32 v10, 0xb0, v158
	v_mad_i64_i32 v[10:11], s[28:29], v10, s49, v[146:147]
	v_cvt_pk_bf16_f32 v21, v12, v13
	global_store_dwordx4 v[34:35], v[18:21], off offset:256
	s_nop 1
	v_lshl_add_u64 v[18:19], v[10:11], 0, v[148:149]
	v_cvt_pk_bf16_f32 v10, v22, v23
	v_cvt_pk_bf16_f32 v11, v24, v25
	v_cvt_pk_bf16_f32 v12, v14, v15
	v_cvt_pk_bf16_f32 v13, v16, v17
	global_store_dwordx4 v[18:19], v[10:13], off
	v_cvt_pk_bf16_f32 v6, v6, v7
	v_cvt_pk_bf16_f32 v7, v8, v9
	v_cvt_pk_bf16_f32 v8, v2, v3
	v_cvt_pk_bf16_f32 v9, v4, v5
	global_store_dwordx4 v[18:19], v[6:9], off offset:256
	s_cbranch_vccnz .LBB0_212
	s_andn2_b64 vcc, exec, s[12:13]
	s_cbranch_vccnz .LBB0_211
	s_barrier
	s_branch .LBB0_211

; __device__ __forceinline__ unsigned cvt_pk_bf16(float lo, float hi) { unsigned r; asm volatile("v_cvt_pk_bf16_f32 %0, %1, %2" : "=v"(r) : "v"(lo), "v"(hi)); return r; }
;     __device__ __forceinline__ void operator()(const pg8::f32x4 (&acc)[2][2][4][2], const pg8::Unit& u, int wr, int wc, int fr, int fq) const {
;         const int row0 = NMETA + u.pm * 256 + wr * 64 + fr, col0 = u.pn * 256 + wc * 32 + 8 * fq;
; #pragma unroll
;         for (int ai = 0; ai < 2; ++ai)
; #pragma unroll
;             for (int m = 0; m < 4; ++m) { bf16_t* rowp = O + (size_t)(row0 + ai * 128 + m * 16) * DFF + col0;
; #pragma unroll
;                 for (int bj = 0; bj < 2; ++bj) { pg8::f32x4 v0 = acc[ai][bj][m][0], v1 = acc[ai][bj][m][1];
; #pragma unroll
;                     for (int i = 0; i < 4; ++i) { const float a = fmaxf(v0[i], 0.f), b = fmaxf(v1[i], 0.f); v0[i] = a * a; v1[i] = b * b; }
;                     u32x4 w; w.x = cvt_pk_bf16(v0[0], v0[1]); w.y = cvt_pk_bf16(v0[2], v0[3]); w.z = cvt_pk_bf16(v1[0], v1[1]); w.w = cvt_pk_bf16(v1[2], v1[3]);
;                     *(u32x4*)(rowp + bj * 128) = w; } }
.LBB0_1293:
	v_lshl_add_u32 v154, s42, 8, v1
	v_max_f32_e32 v122, v122, v122
	v_ashrrev_i32_e32 v155, 31, v154
	v_max_f32_e32 v122, 0, v122
	v_max_f32_e32 v123, v123, v123
	v_max_f32_e32 v124, v124, v124
	v_lshl_or_b32 v146, s68, 8, v148
	v_lshlrev_b64 v[156:157], 14, v[154:155]
	v_mul_f32_e32 v155, v122, v122
	v_max_f32_e32 v122, v127, v127
	v_max_f32_e32 v123, 0, v123
	v_max_f32_e32 v124, 0, v124
	v_ashrrev_i32_e32 v147, 31, v146
	v_max_f32_e32 v126, v126, v126
	v_max_f32_e32 v122, 0, v122
	v_mul_f32_e32 v127, v123, v123
	v_max_f32_e32 v123, v128, v128
	v_mul_f32_e32 v128, v124, v124
	v_max_f32_e32 v124, v129, v129
	v_max_f32_e32 v125, v125, v125
	v_lshl_add_u64 v[156:157], s[10:11], 0, v[156:157]
	v_lshlrev_b64 v[158:159], 1, v[146:147]
	v_max_f32_e32 v126, 0, v126
	v_mul_f32_e32 v122, v122, v122
	v_max_f32_e32 v123, 0, v123
	v_max_f32_e32 v124, 0, v124
	v_max_f32_e32 v125, 0, v125
	v_max_f32_e32 v114, v114, v114
	v_max_f32_e32 v115, v115, v115
	v_max_f32_e32 v116, v116, v116
	v_lshl_add_u64 v[146:147], v[156:157], 0, v[158:159]
	v_mul_f32_e32 v126, v126, v126
	v_mul_f32_e32 v123, v123, v123
	v_mul_f32_e32 v124, v124, v124
	v_mul_f32_e32 v125, v125, v125
	v_cvt_pk_bf16_f32 v122, v126, v122
	v_max_f32_e32 v114, 0, v114
	v_max_f32_e32 v115, 0, v115
	v_max_f32_e32 v116, 0, v116
	v_cvt_pk_bf16_f32 v123, v123, v124
	v_cvt_pk_bf16_f32 v124, v155, v127
	v_cvt_pk_bf16_f32 v125, v128, v125
	global_store_dwordx4 v[146:147], v[122:125], off nt
	v_max_f32_e32 v118, v118, v118
	v_max_f32_e32 v117, v117, v117
	v_mul_f32_e32 v122, v114, v114
	v_max_f32_e32 v114, v119, v119
	v_mul_f32_e32 v119, v115, v115
	v_max_f32_e32 v115, v120, v120
	v_mul_f32_e32 v120, v116, v116
	v_max_f32_e32 v116, v121, v121
	v_max_f32_e32 v114, 0, v114
	v_max_f32_e32 v115, 0, v115
	v_max_f32_e32 v116, 0, v116
	v_max_f32_e32 v118, 0, v118
	v_mul_f32_e32 v114, v114, v114
	v_mul_f32_e32 v115, v115, v115
	v_max_f32_e32 v117, 0, v117
	v_mul_f32_e32 v116, v116, v116
	v_max_f32_e32 v106, v106, v106
	v_mul_f32_e32 v118, v118, v118
	v_mul_f32_e32 v117, v117, v117
	v_cvt_pk_bf16_f32 v114, v118, v114
	v_cvt_pk_bf16_f32 v115, v115, v116
	v_cvt_pk_bf16_f32 v116, v122, v119
	v_max_f32_e32 v106, 0, v106
	v_max_f32_e32 v107, v107, v107
	v_max_f32_e32 v108, v108, v108
	v_cvt_pk_bf16_f32 v117, v120, v117
	global_store_dwordx4 v[146:147], v[114:117], off offset:256 nt
	v_max_f32_e32 v110, v110, v110
	v_max_f32_e32 v107, 0, v107
	v_mul_f32_e32 v116, v106, v106
	v_max_f32_e32 v106, v111, v111
	v_max_f32_e32 v108, 0, v108
	v_max_f32_e32 v110, 0, v110
	v_max_f32_e32 v106, 0, v106
	v_mul_f32_e32 v111, v107, v107
	v_max_f32_e32 v107, v112, v112
	v_mul_f32_e32 v112, v108, v108
	v_max_f32_e32 v108, v113, v113
	v_mul_f32_e32 v110, v110, v110
	v_mul_f32_e32 v106, v106, v106
	v_max_f32_e32 v107, 0, v107
	v_max_f32_e32 v108, 0, v108
	v_max_f32_e32 v109, v109, v109
	v_mul_f32_e32 v107, v107, v107
	v_max_f32_e32 v109, 0, v109
	v_mul_f32_e32 v108, v108, v108
	v_cvt_pk_bf16_f32 v106, v110, v106
	v_add_co_u32_e32 v110, vcc, s60, v146
	v_max_f32_e32 v98, v98, v98
	v_mul_f32_e32 v109, v109, v109
	v_cvt_pk_bf16_f32 v107, v107, v108
	v_cvt_pk_bf16_f32 v108, v116, v111
	v_addc_co_u32_e32 v111, vcc, 0, v147, vcc
	v_max_f32_e32 v98, 0, v98
	v_max_f32_e32 v99, v99, v99
	v_max_f32_e32 v100, v100, v100
	v_cvt_pk_bf16_f32 v109, v112, v109
	global_store_dwordx4 v[110:111], v[106:109], off nt
	v_max_f32_e32 v99, 0, v99
	v_max_f32_e32 v100, 0, v100
	v_mul_f32_e32 v106, v98, v98
	v_max_f32_e32 v98, v103, v103
	v_max_f32_e32 v102, v102, v102
	v_max_f32_e32 v98, 0, v98
	v_mul_f32_e32 v103, v99, v99
	v_max_f32_e32 v99, v104, v104
	v_mul_f32_e32 v104, v100, v100
	v_max_f32_e32 v100, v105, v105
	v_max_f32_e32 v101, v101, v101
	v_max_f32_e32 v102, 0, v102
	v_mul_f32_e32 v98, v98, v98
	v_max_f32_e32 v99, 0, v99
	v_max_f32_e32 v100, 0, v100
	v_max_f32_e32 v101, 0, v101
	v_lshl_add_u64 v[114:115], v[146:147], 0, s[18:19]
	v_mul_f32_e32 v102, v102, v102
	v_mul_f32_e32 v99, v99, v99
	v_mul_f32_e32 v100, v100, v100
	v_mul_f32_e32 v101, v101, v101
	v_cvt_pk_bf16_f32 v98, v102, v98
	v_max_f32_e32 v90, v90, v90
	v_cvt_pk_bf16_f32 v99, v99, v100
	v_cvt_pk_bf16_f32 v100, v106, v103
	v_cvt_pk_bf16_f32 v101, v104, v101
	global_store_dwordx4 v[114:115], v[98:101], off offset:256 nt
	v_max_f32_e32 v90, 0, v90
	v_max_f32_e32 v91, v91, v91
	v_or_b32_e32 v98, 32, v154
	v_max_f32_e32 v92, v92, v92
	v_ashrrev_i32_e32 v99, 31, v98
	v_mul_f32_e32 v100, v90, v90
	v_max_f32_e32 v90, v95, v95
	v_max_f32_e32 v91, 0, v91
	v_max_f32_e32 v92, 0, v92
	v_lshlrev_b64 v[98:99], 14, v[98:99]
	v_max_f32_e32 v94, v94, v94
	v_max_f32_e32 v90, 0, v90
	v_mul_f32_e32 v95, v91, v91
	v_max_f32_e32 v91, v96, v96
	v_mul_f32_e32 v96, v92, v92
	v_max_f32_e32 v92, v97, v97
	v_max_f32_e32 v93, v93, v93
	v_lshl_add_u64 v[98:99], s[10:11], 0, v[98:99]
	v_max_f32_e32 v94, 0, v94
	v_mul_f32_e32 v90, v90, v90
	v_max_f32_e32 v91, 0, v91
	v_max_f32_e32 v92, 0, v92
	v_max_f32_e32 v93, 0, v93
	v_max_f32_e32 v82, v82, v82
	v_max_f32_e32 v83, v83, v83
	v_max_f32_e32 v84, v84, v84
	v_lshl_add_u64 v[98:99], v[98:99], 0, v[158:159]
	v_mul_f32_e32 v94, v94, v94
	v_mul_f32_e32 v91, v91, v91
	v_mul_f32_e32 v92, v92, v92
	v_mul_f32_e32 v93, v93, v93
	v_cvt_pk_bf16_f32 v90, v94, v90
	v_max_f32_e32 v82, 0, v82
	v_max_f32_e32 v83, 0, v83
	v_max_f32_e32 v84, 0, v84
	v_cvt_pk_bf16_f32 v91, v91, v92
	v_cvt_pk_bf16_f32 v92, v100, v95
	v_cvt_pk_bf16_f32 v93, v96, v93
	global_store_dwordx4 v[98:99], v[90:93], off nt
	v_max_f32_e32 v86, v86, v86
	v_max_f32_e32 v85, v85, v85
	v_mul_f32_e32 v90, v82, v82
	v_max_f32_e32 v82, v87, v87
	v_mul_f32_e32 v87, v83, v83
	v_max_f32_e32 v83, v88, v88
; __device__ __forceinline__ unsigned cvt_pk_bf16(float lo, float hi) { unsigned r; asm volatile("v_cvt_pk_bf16_f32 %0, %1, %2" : "=v"(r) : "v"(lo), "v"(hi)); return r; }
;     __device__ __forceinline__ void operator()(const pg8::f32x4 (&acc)[2][2][4][2], const pg8::Unit& u, int wr, int wc, int fr, int fq) const {
;         const int row0 = NMETA + u.pm * 256 + wr * 64 + fr, col0 = u.pn * 256 + wc * 32 + 8 * fq;
; #pragma unroll
;         for (int ai = 0; ai < 2; ++ai)
; #pragma unroll
;             for (int m = 0; m < 4; ++m) { bf16_t* rowp = O + (size_t)(row0 + ai * 128 + m * 16) * DFF + col0;
; #pragma unroll
;                 for (int bj = 0; bj < 2; ++bj) { pg8::f32x4 v0 = acc[ai][bj][m][0], v1 = acc[ai][bj][m][1];
; #pragma unroll
;                     for (int i = 0; i < 4; ++i) { const float a = fmaxf(v0[i], 0.f), b = fmaxf(v1[i], 0.f); v0[i] = a * a; v1[i] = b * b; }
;                     u32x4 w; w.x = cvt_pk_bf16(v0[0], v0[1]); w.y = cvt_pk_bf16(v0[2], v0[3]); w.z = cvt_pk_bf16(v1[0], v1[1]); w.w = cvt_pk_bf16(v1[2], v1[3]);
;                     *(u32x4*)(rowp + bj * 128) = w; } }
;     }
	v_mul_f32_e32 v88, v84, v84
	v_max_f32_e32 v84, v89, v89
	v_max_f32_e32 v82, 0, v82
	v_max_f32_e32 v83, 0, v83
	v_max_f32_e32 v84, 0, v84
	v_max_f32_e32 v86, 0, v86
	v_mul_f32_e32 v82, v82, v82
	v_mul_f32_e32 v83, v83, v83
	v_max_f32_e32 v85, 0, v85
	v_mul_f32_e32 v84, v84, v84
	v_max_f32_e32 v74, v74, v74
	v_mul_f32_e32 v86, v86, v86
	v_mul_f32_e32 v85, v85, v85
	v_cvt_pk_bf16_f32 v82, v86, v82
	v_cvt_pk_bf16_f32 v83, v83, v84
	v_cvt_pk_bf16_f32 v84, v90, v87
	v_max_f32_e32 v74, 0, v74
	v_max_f32_e32 v75, v75, v75
	v_max_f32_e32 v76, v76, v76
	v_cvt_pk_bf16_f32 v85, v88, v85
	global_store_dwordx4 v[98:99], v[82:85], off offset:256 nt
	v_max_f32_e32 v78, v78, v78
	v_max_f32_e32 v75, 0, v75
	v_mul_f32_e32 v84, v74, v74
	v_max_f32_e32 v74, v79, v79
	v_max_f32_e32 v76, 0, v76
	v_max_f32_e32 v78, 0, v78
	v_max_f32_e32 v74, 0, v74
	v_mul_f32_e32 v79, v75, v75
	v_max_f32_e32 v75, v80, v80
	v_mul_f32_e32 v80, v76, v76
	v_max_f32_e32 v76, v81, v81
	v_mul_f32_e32 v78, v78, v78
	v_mul_f32_e32 v74, v74, v74
	v_max_f32_e32 v75, 0, v75
	v_max_f32_e32 v76, 0, v76
	v_max_f32_e32 v77, v77, v77
	v_mul_f32_e32 v75, v75, v75
	v_max_f32_e32 v77, 0, v77
	v_mul_f32_e32 v76, v76, v76
	v_cvt_pk_bf16_f32 v74, v78, v74
	v_add_co_u32_e32 v78, vcc, s61, v146
	v_max_f32_e32 v66, v66, v66
	v_max_f32_e32 v67, v67, v67
	v_max_f32_e32 v68, v68, v68
	v_mul_f32_e32 v77, v77, v77
	v_cvt_pk_bf16_f32 v75, v75, v76
	v_cvt_pk_bf16_f32 v76, v84, v79
	v_addc_co_u32_e32 v79, vcc, 0, v147, vcc
	v_max_f32_e32 v66, 0, v66
	v_max_f32_e32 v67, 0, v67
	v_max_f32_e32 v68, 0, v68
	v_cvt_pk_bf16_f32 v77, v80, v77
	global_store_dwordx4 v[78:79], v[74:77], off nt
	v_max_f32_e32 v70, v70, v70
	v_max_f32_e32 v69, v69, v69
	v_mul_f32_e32 v74, v66, v66
	v_max_f32_e32 v66, v71, v71
	v_mul_f32_e32 v71, v67, v67
	v_max_f32_e32 v67, v72, v72
	v_mul_f32_e32 v72, v68, v68
	v_max_f32_e32 v68, v73, v73
	v_max_f32_e32 v66, 0, v66
	v_max_f32_e32 v67, 0, v67
	v_max_f32_e32 v68, 0, v68
	v_max_f32_e32 v70, 0, v70
	v_mul_f32_e32 v66, v66, v66
	v_mul_f32_e32 v67, v67, v67
	v_max_f32_e32 v69, 0, v69
	v_mul_f32_e32 v68, v68, v68
	v_max_f32_e32 v58, v58, v58
	v_lshl_add_u64 v[82:83], v[146:147], 0, s[20:21]
	v_mul_f32_e32 v70, v70, v70
	v_mul_f32_e32 v69, v69, v69
	v_cvt_pk_bf16_f32 v66, v70, v66
	v_cvt_pk_bf16_f32 v67, v67, v68
	v_cvt_pk_bf16_f32 v68, v74, v71
	v_max_f32_e32 v58, 0, v58
	v_max_f32_e32 v59, v59, v59
	v_max_f32_e32 v60, v60, v60
	v_cvt_pk_bf16_f32 v69, v72, v69
	global_store_dwordx4 v[82:83], v[66:69], off offset:256 nt
	v_max_f32_e32 v62, v62, v62
	v_max_f32_e32 v59, 0, v59
	v_mul_f32_e32 v68, v58, v58
	v_max_f32_e32 v58, v63, v63
	v_max_f32_e32 v60, 0, v60
	v_max_f32_e32 v62, 0, v62
	v_max_f32_e32 v58, 0, v58
	v_mul_f32_e32 v63, v59, v59
	v_max_f32_e32 v59, v64, v64
	v_mul_f32_e32 v64, v60, v60
	v_max_f32_e32 v60, v65, v65
	v_mul_f32_e32 v62, v62, v62
	v_mul_f32_e32 v58, v58, v58
	v_max_f32_e32 v59, 0, v59
	v_max_f32_e32 v60, 0, v60
	v_max_f32_e32 v61, v61, v61
	v_mul_f32_e32 v59, v59, v59
	v_max_f32_e32 v61, 0, v61
	v_mul_f32_e32 v60, v60, v60
	v_cvt_pk_bf16_f32 v58, v62, v58
	v_add_co_u32_e32 v62, vcc, s62, v146
	v_max_f32_e32 v50, v50, v50
	v_max_f32_e32 v51, v51, v51
	v_max_f32_e32 v52, v52, v52
	v_mul_f32_e32 v61, v61, v61
	v_cvt_pk_bf16_f32 v59, v59, v60
	v_cvt_pk_bf16_f32 v60, v68, v63
	v_addc_co_u32_e32 v63, vcc, 0, v147, vcc
	v_max_f32_e32 v50, 0, v50
	v_max_f32_e32 v51, 0, v51
	v_max_f32_e32 v52, 0, v52
	v_cvt_pk_bf16_f32 v61, v64, v61
	global_store_dwordx4 v[62:63], v[58:61], off nt
	v_max_f32_e32 v54, v54, v54
	v_max_f32_e32 v53, v53, v53
	v_mul_f32_e32 v58, v50, v50
	v_max_f32_e32 v50, v55, v55
	v_mul_f32_e32 v55, v51, v51
	v_max_f32_e32 v51, v56, v56
	v_mul_f32_e32 v56, v52, v52
	v_max_f32_e32 v52, v57, v57
	v_max_f32_e32 v50, 0, v50
	v_max_f32_e32 v51, 0, v51
	v_max_f32_e32 v52, 0, v52
	v_max_f32_e32 v54, 0, v54
	v_mul_f32_e32 v50, v50, v50
	v_mul_f32_e32 v51, v51, v51
	v_max_f32_e32 v53, 0, v53
	v_mul_f32_e32 v52, v52, v52
	v_max_f32_e32 v42, v42, v42
	v_lshl_add_u64 v[66:67], v[146:147], 0, s[22:23]
	v_mul_f32_e32 v54, v54, v54
	v_mul_f32_e32 v53, v53, v53
	v_cvt_pk_bf16_f32 v50, v54, v50
	v_cvt_pk_bf16_f32 v51, v51, v52
	v_cvt_pk_bf16_f32 v52, v58, v55
	v_max_f32_e32 v42, 0, v42
	v_max_f32_e32 v43, v43, v43
	v_max_f32_e32 v44, v44, v44
	v_cvt_pk_bf16_f32 v53, v56, v53
	global_store_dwordx4 v[66:67], v[50:53], off offset:256 nt
	v_max_f32_e32 v46, v46, v46
	v_max_f32_e32 v43, 0, v43
	v_mul_f32_e32 v52, v42, v42
	v_max_f32_e32 v42, v47, v47
	v_max_f32_e32 v44, 0, v44
	v_max_f32_e32 v46, 0, v46
	v_max_f32_e32 v42, 0, v42
	v_mul_f32_e32 v47, v43, v43
	v_max_f32_e32 v43, v48, v48
	v_mul_f32_e32 v48, v44, v44
	v_max_f32_e32 v44, v49, v49
	v_mul_f32_e32 v46, v46, v46
	v_mul_f32_e32 v42, v42, v42
	v_max_f32_e32 v43, 0, v43
	v_max_f32_e32 v44, 0, v44
	v_max_f32_e32 v45, v45, v45
	v_mul_f32_e32 v43, v43, v43
	v_max_f32_e32 v45, 0, v45
	v_mul_f32_e32 v44, v44, v44
	v_cvt_pk_bf16_f32 v42, v46, v42
	v_add_co_u32_e32 v46, vcc, s63, v146
; #define PG8_BAR __builtin_amdgcn_s_barrier()
; __device__ __forceinline__ unsigned cvt_pk_bf16(float lo, float hi) { unsigned r; asm volatile("v_cvt_pk_bf16_f32 %0, %1, %2" : "=v"(r) : "v"(lo), "v"(hi)); return r; }
; template <class Epi, class Sched, bool ALIGN_EPI = false, bool SP2 = false>
; __device__ __forceinline__ void gemm_phase(PG8_LAS unsigned char* lds, const Gemm g, const Sched& S, const Epi& E) {
;     ...
;         if constexpr (ALIGN_EPI) { if (wr == 0) PG8_BAR; }
;         if constexpr (!Epi::AFTER_DRAIN) { E(acc, cur, wr, wc, fr, fq); S.done(cur); }
;         if (!has_next) break;
; #pragma unroll
;         for (int a = 0; a < 2; ++a)
; #pragma unroll
;             for (int b = 0; b < 2; ++b)
; #pragma unroll
;                 for (int m = 0; m < 4; ++m)
; #pragma unroll
;                     for (int n = 0; n < 2; ++n) acc[a][b][m][n] = (f32x4){0.f, 0.f, 0.f, 0.f};
;         cur = nxt; cA = nA; cB = nB; ++ui;
;         if constexpr (ALIGN_EPI) { if (wr == 1) PG8_BAR; }
;     }
;     __device__ __forceinline__ void operator()(const pg8::f32x4 (&acc)[2][2][4][2], const pg8::Unit& u, int wr, int wc, int fr, int fq) const {
;         const int row0 = NMETA + u.pm * 256 + wr * 64 + fr, col0 = u.pn * 256 + wc * 32 + 8 * fq;
; #pragma unroll
;         for (int ai = 0; ai < 2; ++ai)
; #pragma unroll
;             for (int m = 0; m < 4; ++m) { bf16_t* rowp = O + (size_t)(row0 + ai * 128 + m * 16) * DFF + col0;
; #pragma unroll
;                 for (int bj = 0; bj < 2; ++bj) { pg8::f32x4 v0 = acc[ai][bj][m][0], v1 = acc[ai][bj][m][1];
; #pragma unroll
;                     for (int i = 0; i < 4; ++i) { const float a = fmaxf(v0[i], 0.f), b = fmaxf(v1[i], 0.f); v0[i] = a * a; v1[i] = b * b; }
;                     u32x4 w; w.x = cvt_pk_bf16(v0[0], v0[1]); w.y = cvt_pk_bf16(v0[2], v0[3]); w.z = cvt_pk_bf16(v1[0], v1[1]); w.w = cvt_pk_bf16(v1[2], v1[3]);
;                     *(u32x4*)(rowp + bj * 128) = w; } }
;     }
	v_max_f32_e32 v34, v34, v34
	v_max_f32_e32 v35, v35, v35
	v_max_f32_e32 v36, v36, v36
	v_mul_f32_e32 v45, v45, v45
	v_cvt_pk_bf16_f32 v43, v43, v44
	v_cvt_pk_bf16_f32 v44, v52, v47
	v_addc_co_u32_e32 v47, vcc, 0, v147, vcc
	v_max_f32_e32 v34, 0, v34
	v_max_f32_e32 v35, 0, v35
	v_max_f32_e32 v36, 0, v36
	v_cvt_pk_bf16_f32 v45, v48, v45
	global_store_dwordx4 v[46:47], v[42:45], off nt
	v_max_f32_e32 v38, v38, v38
	v_max_f32_e32 v37, v37, v37
	v_mul_f32_e32 v42, v34, v34
	v_max_f32_e32 v34, v39, v39
	v_mul_f32_e32 v39, v35, v35
	v_max_f32_e32 v35, v40, v40
	v_mul_f32_e32 v40, v36, v36
	v_max_f32_e32 v36, v41, v41
	v_max_f32_e32 v34, 0, v34
	v_max_f32_e32 v35, 0, v35
	v_max_f32_e32 v36, 0, v36
	v_max_f32_e32 v38, 0, v38
	v_mul_f32_e32 v34, v34, v34
	v_mul_f32_e32 v35, v35, v35
	v_max_f32_e32 v37, 0, v37
	v_mul_f32_e32 v36, v36, v36
	v_max_f32_e32 v26, v26, v26
	v_lshl_add_u64 v[50:51], v[146:147], 0, s[24:25]
	v_mul_f32_e32 v38, v38, v38
	v_mul_f32_e32 v37, v37, v37
	v_cvt_pk_bf16_f32 v34, v38, v34
	v_cvt_pk_bf16_f32 v35, v35, v36
	v_cvt_pk_bf16_f32 v36, v42, v39
	v_max_f32_e32 v26, 0, v26
	v_max_f32_e32 v27, v27, v27
	v_max_f32_e32 v28, v28, v28
	v_cvt_pk_bf16_f32 v37, v40, v37
	global_store_dwordx4 v[50:51], v[34:37], off offset:256 nt
	v_max_f32_e32 v30, v30, v30
	v_max_f32_e32 v27, 0, v27
	v_mul_f32_e32 v36, v26, v26
	v_max_f32_e32 v26, v31, v31
	v_max_f32_e32 v28, 0, v28
	v_max_f32_e32 v30, 0, v30
	v_max_f32_e32 v26, 0, v26
	v_mul_f32_e32 v31, v27, v27
	v_max_f32_e32 v27, v32, v32
	v_mul_f32_e32 v32, v28, v28
	v_max_f32_e32 v28, v33, v33
	v_mul_f32_e32 v30, v30, v30
	v_mul_f32_e32 v26, v26, v26
	v_max_f32_e32 v27, 0, v27
	v_max_f32_e32 v28, 0, v28
	v_max_f32_e32 v29, v29, v29
	v_mul_f32_e32 v27, v27, v27
	v_max_f32_e32 v29, 0, v29
	v_mul_f32_e32 v28, v28, v28
	v_cvt_pk_bf16_f32 v26, v30, v26
	v_add_co_u32_e32 v30, vcc, s64, v146
	v_max_f32_e32 v18, v18, v18
	v_max_f32_e32 v19, v19, v19
	v_max_f32_e32 v20, v20, v20
	v_mul_f32_e32 v29, v29, v29
	v_cvt_pk_bf16_f32 v27, v27, v28
	v_cvt_pk_bf16_f32 v28, v36, v31
	v_addc_co_u32_e32 v31, vcc, 0, v147, vcc
	v_max_f32_e32 v18, 0, v18
	v_max_f32_e32 v19, 0, v19
	v_max_f32_e32 v20, 0, v20
	v_cvt_pk_bf16_f32 v29, v32, v29
	global_store_dwordx4 v[30:31], v[26:29], off nt
	v_max_f32_e32 v22, v22, v22
	v_max_f32_e32 v21, v21, v21
	v_mul_f32_e32 v26, v18, v18
	v_max_f32_e32 v18, v23, v23
	v_mul_f32_e32 v23, v19, v19
	v_max_f32_e32 v19, v24, v24
	v_mul_f32_e32 v24, v20, v20
	v_max_f32_e32 v20, v25, v25
	v_max_f32_e32 v18, 0, v18
	v_max_f32_e32 v19, 0, v19
	v_max_f32_e32 v20, 0, v20
	v_max_f32_e32 v22, 0, v22
	v_mul_f32_e32 v18, v18, v18
	v_mul_f32_e32 v19, v19, v19
	v_max_f32_e32 v21, 0, v21
	v_mul_f32_e32 v20, v20, v20
	v_max_f32_e32 v10, v10, v10
	v_lshl_add_u64 v[34:35], v[146:147], 0, s[26:27]
	v_mul_f32_e32 v22, v22, v22
	v_mul_f32_e32 v21, v21, v21
	v_cvt_pk_bf16_f32 v18, v22, v18
	v_cvt_pk_bf16_f32 v19, v19, v20
	v_cvt_pk_bf16_f32 v20, v26, v23
	v_max_f32_e32 v10, 0, v10
	v_max_f32_e32 v11, v11, v11
	v_max_f32_e32 v12, v12, v12
	v_cvt_pk_bf16_f32 v21, v24, v21
	global_store_dwordx4 v[34:35], v[18:21], off offset:256 nt
	v_max_f32_e32 v14, v14, v14
	v_max_f32_e32 v11, 0, v11
	v_mul_f32_e32 v20, v10, v10
	v_max_f32_e32 v10, v15, v15
	v_max_f32_e32 v12, 0, v12
	v_max_f32_e32 v14, 0, v14
	v_max_f32_e32 v10, 0, v10
	v_mul_f32_e32 v15, v11, v11
	v_max_f32_e32 v11, v16, v16
	v_mul_f32_e32 v16, v12, v12
	v_max_f32_e32 v12, v17, v17
	v_mul_f32_e32 v14, v14, v14
	v_mul_f32_e32 v10, v10, v10
	v_max_f32_e32 v11, 0, v11
	v_max_f32_e32 v12, 0, v12
	v_max_f32_e32 v13, v13, v13
	v_mul_f32_e32 v11, v11, v11
	v_max_f32_e32 v13, 0, v13
	v_mul_f32_e32 v12, v12, v12
	v_cvt_pk_bf16_f32 v10, v14, v10
	v_add_co_u32_e32 v14, vcc, s65, v146
	v_max_f32_e32 v2, v2, v2
	v_max_f32_e32 v3, v3, v3
	v_max_f32_e32 v4, v4, v4
	v_mul_f32_e32 v13, v13, v13
	v_cvt_pk_bf16_f32 v11, v11, v12
	v_cvt_pk_bf16_f32 v12, v20, v15
	v_addc_co_u32_e32 v15, vcc, 0, v147, vcc
	v_max_f32_e32 v2, 0, v2
	v_max_f32_e32 v3, 0, v3
	v_max_f32_e32 v4, 0, v4
	v_cvt_pk_bf16_f32 v13, v16, v13
	global_store_dwordx4 v[14:15], v[10:13], off nt
	v_max_f32_e32 v5, v5, v5
	v_max_f32_e32 v6, v6, v6
	v_mul_f32_e32 v10, v2, v2
	v_max_f32_e32 v2, v7, v7
	v_mul_f32_e32 v7, v3, v3
	v_max_f32_e32 v3, v8, v8
	v_mul_f32_e32 v8, v4, v4
	v_max_f32_e32 v4, v9, v9
	v_max_f32_e32 v2, 0, v2
	v_max_f32_e32 v3, 0, v3
	v_max_f32_e32 v4, 0, v4
	v_max_f32_e32 v5, 0, v5
	v_lshl_add_u64 v[18:19], v[146:147], 0, s[28:29]
	v_max_f32_e32 v6, 0, v6
	v_mul_f32_e32 v2, v2, v2
	v_mul_f32_e32 v3, v3, v3
	v_mul_f32_e32 v4, v4, v4
	v_mul_f32_e32 v5, v5, v5
	s_andn2_b64 vcc, exec, s[6:7]
	s_mov_b64 s[6:7], -1
	v_mul_f32_e32 v6, v6, v6
	v_cvt_pk_bf16_f32 v2, v6, v2
	v_cvt_pk_bf16_f32 v3, v3, v4
	v_cvt_pk_bf16_f32 v4, v10, v7
	v_cvt_pk_bf16_f32 v5, v8, v5
	global_store_dwordx4 v[18:19], v[2:5], off offset:256 nt
	s_cbranch_vccnz .LBB0_1282
	s_andn2_b64 vcc, exec, s[12:13]
	s_cbranch_vccnz .LBB0_1281
	s_barrier
	s_branch .LBB0_1281

; __device__ __forceinline__ unsigned cvt_pk_bf16(float lo, float hi) { unsigned r; asm volatile("v_cvt_pk_bf16_f32 %0, %1, %2" : "=v"(r) : "v"(lo), "v"(hi)); return r; }
;     __device__ __forceinline__ void operator()(const pg8::f32x4 (&acc)[2][2][4][2], const pg8::Unit& u, int wr, int wc, int fr, int fq) const {
;         const int row0 = NMETA + u.pm * 256 + wr * 64 + fr, col0 = u.pn * 256 + wc * 32 + 8 * fq;
; #pragma unroll
;         for (int ai = 0; ai < 2; ++ai)
; #pragma unroll
;             for (int m = 0; m < 4; ++m) { bf16_t* rowp = O + (size_t)(row0 + ai * 128 + m * 16) * PW + col0;
; #pragma unroll
;                 for (int bj = 0; bj < 2; ++bj) { const pg8::f32x4 v0 = acc[ai][bj][m][0], v1 = acc[ai][bj][m][1];
;                     u32x4 w; w.x = cvt_pk_bf16(v0[0], v0[1]); w.y = cvt_pk_bf16(v0[2], v0[3]); w.z = cvt_pk_bf16(v1[0], v1[1]); w.w = cvt_pk_bf16(v1[2], v1[3]);
;                     *(u32x4*)(rowp + bj * 128) = w; } }
;     }
.LBB0_1647:
	v_lshl_or_b32 v148, s54, 8, v150
	v_lshl_add_u32 v158, s28, 8, v1
	v_ashrrev_i32_e32 v149, 31, v148
	v_mov_b64_e32 v[146:147], s[12:13]
	v_mad_i64_i32 v[156:157], s[30:31], v158, s51, v[146:147]
	v_lshlrev_b64 v[148:149], 1, v[148:149]
	v_lshl_add_u64 v[156:157], v[156:157], 0, v[148:149]
	v_cvt_pk_bf16_f32 v126, v126, v127
	v_cvt_pk_bf16_f32 v127, v128, v129
	v_cvt_pk_bf16_f32 v128, v122, v123
	v_cvt_pk_bf16_f32 v129, v124, v125
	global_store_dwordx4 v[156:157], v[126:129], off
	v_cvt_pk_bf16_f32 v114, v114, v115
	v_cvt_pk_bf16_f32 v115, v116, v117
	v_cvt_pk_bf16_f32 v116, v106, v107
	v_add_u32_e32 v106, 16, v158
	v_mad_i64_i32 v[106:107], s[30:31], v106, s51, v[146:147]
	v_cvt_pk_bf16_f32 v117, v108, v109
	global_store_dwordx4 v[156:157], v[114:117], off offset:256
	s_andn2_b64 vcc, exec, s[6:7]
	s_mov_b64 s[6:7], -1
	v_lshl_add_u64 v[114:115], v[106:107], 0, v[148:149]
	v_cvt_pk_bf16_f32 v106, v118, v119
	v_cvt_pk_bf16_f32 v107, v120, v121
	v_cvt_pk_bf16_f32 v108, v110, v111
	v_cvt_pk_bf16_f32 v109, v112, v113
	global_store_dwordx4 v[114:115], v[106:109], off
	v_cvt_pk_bf16_f32 v98, v98, v99
	v_cvt_pk_bf16_f32 v99, v100, v101
	v_cvt_pk_bf16_f32 v100, v90, v91
	v_or_b32_e32 v90, 32, v158
	v_mad_i64_i32 v[90:91], s[30:31], v90, s51, v[146:147]
	v_cvt_pk_bf16_f32 v101, v92, v93
	global_store_dwordx4 v[114:115], v[98:101], off offset:256
	s_nop 1
	v_lshl_add_u64 v[98:99], v[90:91], 0, v[148:149]
	v_cvt_pk_bf16_f32 v90, v102, v103
	v_cvt_pk_bf16_f32 v91, v104, v105
	v_cvt_pk_bf16_f32 v92, v94, v95
	v_cvt_pk_bf16_f32 v93, v96, v97
	global_store_dwordx4 v[98:99], v[90:93], off
	v_cvt_pk_bf16_f32 v82, v82, v83
	v_cvt_pk_bf16_f32 v83, v84, v85
	v_cvt_pk_bf16_f32 v84, v74, v75
	v_add_u32_e32 v74, 48, v158
	v_mad_i64_i32 v[74:75], s[30:31], v74, s51, v[146:147]
	v_cvt_pk_bf16_f32 v85, v76, v77
	global_store_dwordx4 v[98:99], v[82:85], off offset:256
	s_nop 1
	v_lshl_add_u64 v[82:83], v[74:75], 0, v[148:149]
	v_cvt_pk_bf16_f32 v74, v86, v87
	v_cvt_pk_bf16_f32 v75, v88, v89
	v_cvt_pk_bf16_f32 v76, v78, v79
	v_cvt_pk_bf16_f32 v77, v80, v81
	global_store_dwordx4 v[82:83], v[74:77], off
	v_cvt_pk_bf16_f32 v70, v70, v71
	v_cvt_pk_bf16_f32 v71, v72, v73
	v_cvt_pk_bf16_f32 v72, v66, v67
	v_add_u32_e32 v66, 0x80, v158
	v_mad_i64_i32 v[66:67], s[30:31], v66, s51, v[146:147]
	v_lshl_add_u64 v[66:67], v[66:67], 0, v[148:149]
	v_cvt_pk_bf16_f32 v73, v68, v69
	global_store_dwordx4 v[82:83], v[70:73], off offset:256
	v_cvt_pk_bf16_f32 v62, v62, v63
	v_cvt_pk_bf16_f32 v63, v64, v65
	v_cvt_pk_bf16_f32 v64, v58, v59
	v_cvt_pk_bf16_f32 v65, v60, v61
	global_store_dwordx4 v[66:67], v[62:65], off
	v_cvt_pk_bf16_f32 v50, v50, v51
	v_cvt_pk_bf16_f32 v51, v52, v53
	v_cvt_pk_bf16_f32 v52, v42, v43
	v_add_u32_e32 v42, 0x90, v158
	v_mad_i64_i32 v[42:43], s[30:31], v42, s51, v[146:147]
	v_cvt_pk_bf16_f32 v53, v44, v45
	global_store_dwordx4 v[66:67], v[50:53], off offset:256
	s_nop 1
	v_lshl_add_u64 v[50:51], v[42:43], 0, v[148:149]
	v_cvt_pk_bf16_f32 v42, v54, v55
	v_cvt_pk_bf16_f32 v43, v56, v57
	v_cvt_pk_bf16_f32 v44, v46, v47
	v_cvt_pk_bf16_f32 v45, v48, v49
	global_store_dwordx4 v[50:51], v[42:45], off
	v_cvt_pk_bf16_f32 v34, v34, v35
	v_cvt_pk_bf16_f32 v35, v36, v37
	v_cvt_pk_bf16_f32 v36, v26, v27
	v_add_u32_e32 v26, 0xa0, v158
	v_mad_i64_i32 v[26:27], s[30:31], v26, s51, v[146:147]
	v_cvt_pk_bf16_f32 v37, v28, v29
	global_store_dwordx4 v[50:51], v[34:37], off offset:256
	s_nop 1
	v_lshl_add_u64 v[34:35], v[26:27], 0, v[148:149]
	v_cvt_pk_bf16_f32 v26, v38, v39
	v_cvt_pk_bf16_f32 v27, v40, v41
	v_cvt_pk_bf16_f32 v28, v30, v31
	v_cvt_pk_bf16_f32 v29, v32, v33
	global_store_dwordx4 v[34:35], v[26:29], off
	v_cvt_pk_bf16_f32 v18, v18, v19
	v_cvt_pk_bf16_f32 v19, v20, v21
	v_cvt_pk_bf16_f32 v20, v10, v11
	v_add_u32_e32 v10, 0xb0, v158
	v_mad_i64_i32 v[10:11], s[30:31], v10, s51, v[146:147]
	v_cvt_pk_bf16_f32 v21, v12, v13
	global_store_dwordx4 v[34:35], v[18:21], off offset:256
	s_nop 1
	v_lshl_add_u64 v[18:19], v[10:11], 0, v[148:149]
	v_cvt_pk_bf16_f32 v10, v22, v23
	v_cvt_pk_bf16_f32 v11, v24, v25
	v_cvt_pk_bf16_f32 v12, v14, v15
	v_cvt_pk_bf16_f32 v13, v16, v17
	global_store_dwordx4 v[18:19], v[10:13], off
	v_cvt_pk_bf16_f32 v6, v6, v7
	v_cvt_pk_bf16_f32 v7, v8, v9
	v_cvt_pk_bf16_f32 v8, v2, v3
	v_cvt_pk_bf16_f32 v9, v4, v5
	global_store_dwordx4 v[18:19], v[6:9], off offset:256
	s_cbranch_vccnz .LBB0_1640
	s_andn2_b64 vcc, exec, s[14:15]
	s_cbranch_vccnz .LBB0_1639
	s_barrier
	s_branch .LBB0_1639

; __device__ __forceinline__ unsigned cvt_pk_bf16(float lo, float hi) { unsigned r; asm volatile("v_cvt_pk_bf16_f32 %0, %1, %2" : "=v"(r) : "v"(lo), "v"(hi)); return r; }
;     __device__ __forceinline__ void operator()(const pg8::f32x4 (&acc)[2][2][4][2], const pg8::Unit& u, int wr, int wc, int fr, int fq) const {
;         const int row0 = NMETA + u.pm * 256 + wr * 64 + fr, col0 = u.pn * 256 + wc * 32 + 8 * fq;
; #pragma unroll
;         for (int ai = 0; ai < 2; ++ai)
; #pragma unroll
;             for (int m = 0; m < 4; ++m) { bf16_t* rowp = O + (size_t)(row0 + ai * 128 + m * 16) * DFF + col0;
; #pragma unroll
;                 for (int bj = 0; bj < 2; ++bj) { pg8::f32x4 v0 = acc[ai][bj][m][0], v1 = acc[ai][bj][m][1];
; #pragma unroll
;                     for (int i = 0; i < 4; ++i) { const float a = fmaxf(v0[i], 0.f), b = fmaxf(v1[i], 0.f); v0[i] = a * a; v1[i] = b * b; }
;                     u32x4 w; w.x = cvt_pk_bf16(v0[0], v0[1]); w.y = cvt_pk_bf16(v0[2], v0[3]); w.z = cvt_pk_bf16(v1[0], v1[1]); w.w = cvt_pk_bf16(v1[2], v1[3]);
;                     *(u32x4*)(rowp + bj * 128) = w; } }
;     }
.LBB0_2721:
	v_lshl_add_u32 v154, s44, 8, v1
	v_max_f32_e32 v122, v122, v122
	v_ashrrev_i32_e32 v155, 31, v154
	v_max_f32_e32 v122, 0, v122
	v_max_f32_e32 v123, v123, v123
	v_max_f32_e32 v124, v124, v124
	v_lshl_or_b32 v146, s70, 8, v148
	v_lshlrev_b64 v[156:157], 14, v[154:155]
	v_mul_f32_e32 v155, v122, v122
	v_max_f32_e32 v122, v127, v127
	v_max_f32_e32 v123, 0, v123
	v_max_f32_e32 v124, 0, v124
	v_ashrrev_i32_e32 v147, 31, v146
	v_max_f32_e32 v126, v126, v126
	v_max_f32_e32 v122, 0, v122
	v_mul_f32_e32 v127, v123, v123
	v_max_f32_e32 v123, v128, v128
	v_mul_f32_e32 v128, v124, v124
	v_max_f32_e32 v124, v129, v129
	v_max_f32_e32 v125, v125, v125
	v_lshl_add_u64 v[156:157], s[12:13], 0, v[156:157]
	v_lshlrev_b64 v[158:159], 1, v[146:147]
	v_max_f32_e32 v126, 0, v126
	v_mul_f32_e32 v122, v122, v122
	v_max_f32_e32 v123, 0, v123
	v_max_f32_e32 v124, 0, v124
	v_max_f32_e32 v125, 0, v125
	v_max_f32_e32 v114, v114, v114
	v_max_f32_e32 v115, v115, v115
	v_max_f32_e32 v116, v116, v116
	v_lshl_add_u64 v[146:147], v[156:157], 0, v[158:159]
	v_mul_f32_e32 v126, v126, v126
	v_mul_f32_e32 v123, v123, v123
	v_mul_f32_e32 v124, v124, v124
	v_mul_f32_e32 v125, v125, v125
	v_cvt_pk_bf16_f32 v122, v126, v122
	v_max_f32_e32 v114, 0, v114
	v_max_f32_e32 v115, 0, v115
	v_max_f32_e32 v116, 0, v116
	v_cvt_pk_bf16_f32 v123, v123, v124
	v_cvt_pk_bf16_f32 v124, v155, v127
	v_cvt_pk_bf16_f32 v125, v128, v125
	global_store_dwordx4 v[146:147], v[122:125], off nt
	v_max_f32_e32 v118, v118, v118
	v_max_f32_e32 v117, v117, v117
	v_mul_f32_e32 v122, v114, v114
	v_max_f32_e32 v114, v119, v119
	v_mul_f32_e32 v119, v115, v115
	v_max_f32_e32 v115, v120, v120
	v_mul_f32_e32 v120, v116, v116
	v_max_f32_e32 v116, v121, v121
	v_max_f32_e32 v114, 0, v114
	v_max_f32_e32 v115, 0, v115
	v_max_f32_e32 v116, 0, v116
	v_max_f32_e32 v118, 0, v118
	v_mul_f32_e32 v114, v114, v114
	v_mul_f32_e32 v115, v115, v115
	v_max_f32_e32 v117, 0, v117
	v_mul_f32_e32 v116, v116, v116
	v_max_f32_e32 v106, v106, v106
	v_mul_f32_e32 v118, v118, v118
	v_mul_f32_e32 v117, v117, v117
	v_cvt_pk_bf16_f32 v114, v118, v114
	v_cvt_pk_bf16_f32 v115, v115, v116
	v_cvt_pk_bf16_f32 v116, v122, v119
	v_max_f32_e32 v106, 0, v106
	v_max_f32_e32 v107, v107, v107
	v_max_f32_e32 v108, v108, v108
	v_cvt_pk_bf16_f32 v117, v120, v117
	global_store_dwordx4 v[146:147], v[114:117], off offset:256 nt
	v_max_f32_e32 v110, v110, v110
	v_max_f32_e32 v107, 0, v107
	v_mul_f32_e32 v116, v106, v106
	v_max_f32_e32 v106, v111, v111
	v_max_f32_e32 v108, 0, v108
	v_max_f32_e32 v110, 0, v110
	v_max_f32_e32 v106, 0, v106
	v_mul_f32_e32 v111, v107, v107
	v_max_f32_e32 v107, v112, v112
	v_mul_f32_e32 v112, v108, v108
	v_max_f32_e32 v108, v113, v113
	v_mul_f32_e32 v110, v110, v110
	v_mul_f32_e32 v106, v106, v106
	v_max_f32_e32 v107, 0, v107
	v_max_f32_e32 v108, 0, v108
	v_max_f32_e32 v109, v109, v109
	v_mul_f32_e32 v107, v107, v107
	v_max_f32_e32 v109, 0, v109
	v_mul_f32_e32 v108, v108, v108
	v_cvt_pk_bf16_f32 v106, v110, v106
	v_add_co_u32_e32 v110, vcc, s62, v146
	v_max_f32_e32 v98, v98, v98
	v_mul_f32_e32 v109, v109, v109
	v_cvt_pk_bf16_f32 v107, v107, v108
	v_cvt_pk_bf16_f32 v108, v116, v111
	v_addc_co_u32_e32 v111, vcc, 0, v147, vcc
	v_max_f32_e32 v98, 0, v98
	v_max_f32_e32 v99, v99, v99
	v_max_f32_e32 v100, v100, v100
	v_cvt_pk_bf16_f32 v109, v112, v109
	global_store_dwordx4 v[110:111], v[106:109], off nt
	v_max_f32_e32 v99, 0, v99
	v_max_f32_e32 v100, 0, v100
	v_mul_f32_e32 v106, v98, v98
	v_max_f32_e32 v98, v103, v103
	v_max_f32_e32 v102, v102, v102
	v_max_f32_e32 v98, 0, v98
	v_mul_f32_e32 v103, v99, v99
	v_max_f32_e32 v99, v104, v104
	v_mul_f32_e32 v104, v100, v100
	v_max_f32_e32 v100, v105, v105
	v_max_f32_e32 v101, v101, v101
	v_max_f32_e32 v102, 0, v102
	v_mul_f32_e32 v98, v98, v98
	v_max_f32_e32 v99, 0, v99
	v_max_f32_e32 v100, 0, v100
	v_max_f32_e32 v101, 0, v101
	v_lshl_add_u64 v[114:115], v[146:147], 0, s[20:21]
	v_mul_f32_e32 v102, v102, v102
	v_mul_f32_e32 v99, v99, v99
	v_mul_f32_e32 v100, v100, v100
	v_mul_f32_e32 v101, v101, v101
	v_cvt_pk_bf16_f32 v98, v102, v98
	v_max_f32_e32 v90, v90, v90
	v_cvt_pk_bf16_f32 v99, v99, v100
	v_cvt_pk_bf16_f32 v100, v106, v103
	v_cvt_pk_bf16_f32 v101, v104, v101
	global_store_dwordx4 v[114:115], v[98:101], off offset:256 nt
	v_max_f32_e32 v90, 0, v90
	v_max_f32_e32 v91, v91, v91
	v_or_b32_e32 v98, 32, v154
	v_max_f32_e32 v92, v92, v92
	v_ashrrev_i32_e32 v99, 31, v98
	v_mul_f32_e32 v100, v90, v90
	v_max_f32_e32 v90, v95, v95
	v_max_f32_e32 v91, 0, v91
	v_max_f32_e32 v92, 0, v92
	v_lshlrev_b64 v[98:99], 14, v[98:99]
	v_max_f32_e32 v94, v94, v94
	v_max_f32_e32 v90, 0, v90
	v_mul_f32_e32 v95, v91, v91
	v_max_f32_e32 v91, v96, v96
	v_mul_f32_e32 v96, v92, v92
	v_max_f32_e32 v92, v97, v97
	v_max_f32_e32 v93, v93, v93
	v_lshl_add_u64 v[98:99], s[12:13], 0, v[98:99]
	v_max_f32_e32 v94, 0, v94
	v_mul_f32_e32 v90, v90, v90
	v_max_f32_e32 v91, 0, v91
	v_max_f32_e32 v92, 0, v92
	v_max_f32_e32 v93, 0, v93
	v_max_f32_e32 v82, v82, v82
	v_max_f32_e32 v83, v83, v83
	v_max_f32_e32 v84, v84, v84
	v_lshl_add_u64 v[98:99], v[98:99], 0, v[158:159]
	v_mul_f32_e32 v94, v94, v94
	v_mul_f32_e32 v91, v91, v91
	v_mul_f32_e32 v92, v92, v92
	v_mul_f32_e32 v93, v93, v93
	v_cvt_pk_bf16_f32 v90, v94, v90
	v_max_f32_e32 v82, 0, v82
	v_max_f32_e32 v83, 0, v83
	v_max_f32_e32 v84, 0, v84
	v_cvt_pk_bf16_f32 v91, v91, v92
	v_cvt_pk_bf16_f32 v92, v100, v95
	v_cvt_pk_bf16_f32 v93, v96, v93
	global_store_dwordx4 v[98:99], v[90:93], off nt
	v_max_f32_e32 v86, v86, v86
	v_max_f32_e32 v85, v85, v85
	v_mul_f32_e32 v90, v82, v82
	v_max_f32_e32 v82, v87, v87
	v_mul_f32_e32 v87, v83, v83
	v_max_f32_e32 v83, v88, v88
; __device__ __forceinline__ unsigned cvt_pk_bf16(float lo, float hi) { unsigned r; asm volatile("v_cvt_pk_bf16_f32 %0, %1, %2" : "=v"(r) : "v"(lo), "v"(hi)); return r; }
;     __device__ __forceinline__ void operator()(const pg8::f32x4 (&acc)[2][2][4][2], const pg8::Unit& u, int wr, int wc, int fr, int fq) const {
;         const int row0 = NMETA + u.pm * 256 + wr * 64 + fr, col0 = u.pn * 256 + wc * 32 + 8 * fq;
; #pragma unroll
;         for (int ai = 0; ai < 2; ++ai)
; #pragma unroll
;             for (int m = 0; m < 4; ++m) { bf16_t* rowp = O + (size_t)(row0 + ai * 128 + m * 16) * DFF + col0;
; #pragma unroll
;                 for (int bj = 0; bj < 2; ++bj) { pg8::f32x4 v0 = acc[ai][bj][m][0], v1 = acc[ai][bj][m][1];
; #pragma unroll
;                     for (int i = 0; i < 4; ++i) { const float a = fmaxf(v0[i], 0.f), b = fmaxf(v1[i], 0.f); v0[i] = a * a; v1[i] = b * b; }
;                     u32x4 w; w.x = cvt_pk_bf16(v0[0], v0[1]); w.y = cvt_pk_bf16(v0[2], v0[3]); w.z = cvt_pk_bf16(v1[0], v1[1]); w.w = cvt_pk_bf16(v1[2], v1[3]);
;                     *(u32x4*)(rowp + bj * 128) = w; } }
;     }
	v_mul_f32_e32 v88, v84, v84
	v_max_f32_e32 v84, v89, v89
	v_max_f32_e32 v82, 0, v82
	v_max_f32_e32 v83, 0, v83
	v_max_f32_e32 v84, 0, v84
	v_max_f32_e32 v86, 0, v86
	v_mul_f32_e32 v82, v82, v82
	v_mul_f32_e32 v83, v83, v83
	v_max_f32_e32 v85, 0, v85
	v_mul_f32_e32 v84, v84, v84
	v_max_f32_e32 v74, v74, v74
	v_mul_f32_e32 v86, v86, v86
	v_mul_f32_e32 v85, v85, v85
	v_cvt_pk_bf16_f32 v82, v86, v82
	v_cvt_pk_bf16_f32 v83, v83, v84
	v_cvt_pk_bf16_f32 v84, v90, v87
	v_max_f32_e32 v74, 0, v74
	v_max_f32_e32 v75, v75, v75
	v_max_f32_e32 v76, v76, v76
	v_cvt_pk_bf16_f32 v85, v88, v85
	global_store_dwordx4 v[98:99], v[82:85], off offset:256 nt
	v_max_f32_e32 v78, v78, v78
	v_max_f32_e32 v75, 0, v75
	v_mul_f32_e32 v84, v74, v74
	v_max_f32_e32 v74, v79, v79
	v_max_f32_e32 v76, 0, v76
	v_max_f32_e32 v78, 0, v78
	v_max_f32_e32 v74, 0, v74
	v_mul_f32_e32 v79, v75, v75
	v_max_f32_e32 v75, v80, v80
	v_mul_f32_e32 v80, v76, v76
	v_max_f32_e32 v76, v81, v81
	v_mul_f32_e32 v78, v78, v78
	v_mul_f32_e32 v74, v74, v74
	v_max_f32_e32 v75, 0, v75
	v_max_f32_e32 v76, 0, v76
	v_max_f32_e32 v77, v77, v77
	v_mul_f32_e32 v75, v75, v75
	v_max_f32_e32 v77, 0, v77
	v_mul_f32_e32 v76, v76, v76
	v_cvt_pk_bf16_f32 v74, v78, v74
	v_add_co_u32_e32 v78, vcc, s63, v146
	v_max_f32_e32 v66, v66, v66
	v_max_f32_e32 v67, v67, v67
	v_max_f32_e32 v68, v68, v68
	v_mul_f32_e32 v77, v77, v77
	v_cvt_pk_bf16_f32 v75, v75, v76
	v_cvt_pk_bf16_f32 v76, v84, v79
	v_addc_co_u32_e32 v79, vcc, 0, v147, vcc
	v_max_f32_e32 v66, 0, v66
	v_max_f32_e32 v67, 0, v67
	v_max_f32_e32 v68, 0, v68
	v_cvt_pk_bf16_f32 v77, v80, v77
	global_store_dwordx4 v[78:79], v[74:77], off nt
	v_max_f32_e32 v70, v70, v70
	v_max_f32_e32 v69, v69, v69
	v_mul_f32_e32 v74, v66, v66
	v_max_f32_e32 v66, v71, v71
	v_mul_f32_e32 v71, v67, v67
	v_max_f32_e32 v67, v72, v72
	v_mul_f32_e32 v72, v68, v68
	v_max_f32_e32 v68, v73, v73
	v_max_f32_e32 v66, 0, v66
	v_max_f32_e32 v67, 0, v67
	v_max_f32_e32 v68, 0, v68
	v_max_f32_e32 v70, 0, v70
	v_mul_f32_e32 v66, v66, v66
	v_mul_f32_e32 v67, v67, v67
	v_max_f32_e32 v69, 0, v69
	v_mul_f32_e32 v68, v68, v68
	v_max_f32_e32 v58, v58, v58
	v_lshl_add_u64 v[82:83], v[146:147], 0, s[22:23]
	v_mul_f32_e32 v70, v70, v70
	v_mul_f32_e32 v69, v69, v69
	v_cvt_pk_bf16_f32 v66, v70, v66
	v_cvt_pk_bf16_f32 v67, v67, v68
	v_cvt_pk_bf16_f32 v68, v74, v71
	v_max_f32_e32 v58, 0, v58
	v_max_f32_e32 v59, v59, v59
	v_max_f32_e32 v60, v60, v60
	v_cvt_pk_bf16_f32 v69, v72, v69
	global_store_dwordx4 v[82:83], v[66:69], off offset:256 nt
	v_max_f32_e32 v62, v62, v62
	v_max_f32_e32 v59, 0, v59
	v_mul_f32_e32 v68, v58, v58
	v_max_f32_e32 v58, v63, v63
	v_max_f32_e32 v60, 0, v60
	v_max_f32_e32 v62, 0, v62
	v_max_f32_e32 v58, 0, v58
	v_mul_f32_e32 v63, v59, v59
	v_max_f32_e32 v59, v64, v64
	v_mul_f32_e32 v64, v60, v60
	v_max_f32_e32 v60, v65, v65
	v_mul_f32_e32 v62, v62, v62
	v_mul_f32_e32 v58, v58, v58
	v_max_f32_e32 v59, 0, v59
	v_max_f32_e32 v60, 0, v60
	v_max_f32_e32 v61, v61, v61
	v_mul_f32_e32 v59, v59, v59
	v_max_f32_e32 v61, 0, v61
	v_mul_f32_e32 v60, v60, v60
	v_cvt_pk_bf16_f32 v58, v62, v58
	v_add_co_u32_e32 v62, vcc, s64, v146
	v_max_f32_e32 v50, v50, v50
	v_max_f32_e32 v51, v51, v51
	v_max_f32_e32 v52, v52, v52
	v_mul_f32_e32 v61, v61, v61
	v_cvt_pk_bf16_f32 v59, v59, v60
	v_cvt_pk_bf16_f32 v60, v68, v63
	v_addc_co_u32_e32 v63, vcc, 0, v147, vcc
	v_max_f32_e32 v50, 0, v50
	v_max_f32_e32 v51, 0, v51
	v_max_f32_e32 v52, 0, v52
	v_cvt_pk_bf16_f32 v61, v64, v61
	global_store_dwordx4 v[62:63], v[58:61], off nt
	v_max_f32_e32 v54, v54, v54
	v_max_f32_e32 v53, v53, v53
	v_mul_f32_e32 v58, v50, v50
	v_max_f32_e32 v50, v55, v55
	v_mul_f32_e32 v55, v51, v51
	v_max_f32_e32 v51, v56, v56
	v_mul_f32_e32 v56, v52, v52
	v_max_f32_e32 v52, v57, v57
	v_max_f32_e32 v50, 0, v50
	v_max_f32_e32 v51, 0, v51
	v_max_f32_e32 v52, 0, v52
	v_max_f32_e32 v54, 0, v54
	v_mul_f32_e32 v50, v50, v50
	v_mul_f32_e32 v51, v51, v51
	v_max_f32_e32 v53, 0, v53
	v_mul_f32_e32 v52, v52, v52
	v_max_f32_e32 v42, v42, v42
	v_lshl_add_u64 v[66:67], v[146:147], 0, s[24:25]
	v_mul_f32_e32 v54, v54, v54
	v_mul_f32_e32 v53, v53, v53
	v_cvt_pk_bf16_f32 v50, v54, v50
	v_cvt_pk_bf16_f32 v51, v51, v52
	v_cvt_pk_bf16_f32 v52, v58, v55
	v_max_f32_e32 v42, 0, v42
	v_max_f32_e32 v43, v43, v43
	v_max_f32_e32 v44, v44, v44
	v_cvt_pk_bf16_f32 v53, v56, v53
	global_store_dwordx4 v[66:67], v[50:53], off offset:256 nt
	v_max_f32_e32 v46, v46, v46
	v_max_f32_e32 v43, 0, v43
	v_mul_f32_e32 v52, v42, v42
	v_max_f32_e32 v42, v47, v47
	v_max_f32_e32 v44, 0, v44
	v_max_f32_e32 v46, 0, v46
	v_max_f32_e32 v42, 0, v42
	v_mul_f32_e32 v47, v43, v43
	v_max_f32_e32 v43, v48, v48
	v_mul_f32_e32 v48, v44, v44
	v_max_f32_e32 v44, v49, v49
	v_mul_f32_e32 v46, v46, v46
	v_mul_f32_e32 v42, v42, v42
	v_max_f32_e32 v43, 0, v43
	v_max_f32_e32 v44, 0, v44
	v_max_f32_e32 v45, v45, v45
	v_mul_f32_e32 v43, v43, v43
	v_max_f32_e32 v45, 0, v45
	v_mul_f32_e32 v44, v44, v44
	v_cvt_pk_bf16_f32 v42, v46, v42
	v_add_co_u32_e32 v46, vcc, s65, v146
; #define PG8_BAR __builtin_amdgcn_s_barrier()
; __device__ __forceinline__ unsigned cvt_pk_bf16(float lo, float hi) { unsigned r; asm volatile("v_cvt_pk_bf16_f32 %0, %1, %2" : "=v"(r) : "v"(lo), "v"(hi)); return r; }
; template <class Epi, class Sched, bool ALIGN_EPI = false, bool SP2 = false>
; __device__ __forceinline__ void gemm_phase(PG8_LAS unsigned char* lds, const Gemm g, const Sched& S, const Epi& E) {
;     ...
;         if constexpr (ALIGN_EPI) { if (wr == 0) PG8_BAR; }
;         if constexpr (!Epi::AFTER_DRAIN) { E(acc, cur, wr, wc, fr, fq); S.done(cur); }
;         if (!has_next) break;
; #pragma unroll
;         for (int a = 0; a < 2; ++a)
; #pragma unroll
;             for (int b = 0; b < 2; ++b)
; #pragma unroll
;                 for (int m = 0; m < 4; ++m)
; #pragma unroll
;                     for (int n = 0; n < 2; ++n) acc[a][b][m][n] = (f32x4){0.f, 0.f, 0.f, 0.f};
;         cur = nxt; cA = nA; cB = nB; ++ui;
;         if constexpr (ALIGN_EPI) { if (wr == 1) PG8_BAR; }
;     }
;     __device__ __forceinline__ void operator()(const pg8::f32x4 (&acc)[2][2][4][2], const pg8::Unit& u, int wr, int wc, int fr, int fq) const {
;         const int row0 = NMETA + u.pm * 256 + wr * 64 + fr, col0 = u.pn * 256 + wc * 32 + 8 * fq;
; #pragma unroll
;         for (int ai = 0; ai < 2; ++ai)
; #pragma unroll
;             for (int m = 0; m < 4; ++m) { bf16_t* rowp = O + (size_t)(row0 + ai * 128 + m * 16) * DFF + col0;
; #pragma unroll
;                 for (int bj = 0; bj < 2; ++bj) { pg8::f32x4 v0 = acc[ai][bj][m][0], v1 = acc[ai][bj][m][1];
; #pragma unroll
;                     for (int i = 0; i < 4; ++i) { const float a = fmaxf(v0[i], 0.f), b = fmaxf(v1[i], 0.f); v0[i] = a * a; v1[i] = b * b; }
;                     u32x4 w; w.x = cvt_pk_bf16(v0[0], v0[1]); w.y = cvt_pk_bf16(v0[2], v0[3]); w.z = cvt_pk_bf16(v1[0], v1[1]); w.w = cvt_pk_bf16(v1[2], v1[3]);
;                     *(u32x4*)(rowp + bj * 128) = w; } }
;     }
	v_max_f32_e32 v34, v34, v34
	v_max_f32_e32 v35, v35, v35
	v_max_f32_e32 v36, v36, v36
	v_mul_f32_e32 v45, v45, v45
	v_cvt_pk_bf16_f32 v43, v43, v44
	v_cvt_pk_bf16_f32 v44, v52, v47
	v_addc_co_u32_e32 v47, vcc, 0, v147, vcc
	v_max_f32_e32 v34, 0, v34
	v_max_f32_e32 v35, 0, v35
	v_max_f32_e32 v36, 0, v36
	v_cvt_pk_bf16_f32 v45, v48, v45
	global_store_dwordx4 v[46:47], v[42:45], off nt
	v_max_f32_e32 v38, v38, v38
	v_max_f32_e32 v37, v37, v37
	v_mul_f32_e32 v42, v34, v34
	v_max_f32_e32 v34, v39, v39
	v_mul_f32_e32 v39, v35, v35
	v_max_f32_e32 v35, v40, v40
	v_mul_f32_e32 v40, v36, v36
	v_max_f32_e32 v36, v41, v41
	v_max_f32_e32 v34, 0, v34
	v_max_f32_e32 v35, 0, v35
	v_max_f32_e32 v36, 0, v36
	v_max_f32_e32 v38, 0, v38
	v_mul_f32_e32 v34, v34, v34
	v_mul_f32_e32 v35, v35, v35
	v_max_f32_e32 v37, 0, v37
	v_mul_f32_e32 v36, v36, v36
	v_max_f32_e32 v26, v26, v26
	v_lshl_add_u64 v[50:51], v[146:147], 0, s[26:27]
	v_mul_f32_e32 v38, v38, v38
	v_mul_f32_e32 v37, v37, v37
	v_cvt_pk_bf16_f32 v34, v38, v34
	v_cvt_pk_bf16_f32 v35, v35, v36
	v_cvt_pk_bf16_f32 v36, v42, v39
	v_max_f32_e32 v26, 0, v26
	v_max_f32_e32 v27, v27, v27
	v_max_f32_e32 v28, v28, v28
	v_cvt_pk_bf16_f32 v37, v40, v37
	global_store_dwordx4 v[50:51], v[34:37], off offset:256 nt
	v_max_f32_e32 v30, v30, v30
	v_max_f32_e32 v27, 0, v27
	v_mul_f32_e32 v36, v26, v26
	v_max_f32_e32 v26, v31, v31
	v_max_f32_e32 v28, 0, v28
	v_max_f32_e32 v30, 0, v30
	v_max_f32_e32 v26, 0, v26
	v_mul_f32_e32 v31, v27, v27
	v_max_f32_e32 v27, v32, v32
	v_mul_f32_e32 v32, v28, v28
	v_max_f32_e32 v28, v33, v33
	v_mul_f32_e32 v30, v30, v30
	v_mul_f32_e32 v26, v26, v26
	v_max_f32_e32 v27, 0, v27
	v_max_f32_e32 v28, 0, v28
	v_max_f32_e32 v29, v29, v29
	v_mul_f32_e32 v27, v27, v27
	v_max_f32_e32 v29, 0, v29
	v_mul_f32_e32 v28, v28, v28
	v_cvt_pk_bf16_f32 v26, v30, v26
	v_add_co_u32_e32 v30, vcc, s66, v146
	v_max_f32_e32 v18, v18, v18
	v_max_f32_e32 v19, v19, v19
	v_max_f32_e32 v20, v20, v20
	v_mul_f32_e32 v29, v29, v29
	v_cvt_pk_bf16_f32 v27, v27, v28
	v_cvt_pk_bf16_f32 v28, v36, v31
	v_addc_co_u32_e32 v31, vcc, 0, v147, vcc
	v_max_f32_e32 v18, 0, v18
	v_max_f32_e32 v19, 0, v19
	v_max_f32_e32 v20, 0, v20
	v_cvt_pk_bf16_f32 v29, v32, v29
	global_store_dwordx4 v[30:31], v[26:29], off nt
	v_max_f32_e32 v22, v22, v22
	v_max_f32_e32 v21, v21, v21
	v_mul_f32_e32 v26, v18, v18
	v_max_f32_e32 v18, v23, v23
	v_mul_f32_e32 v23, v19, v19
	v_max_f32_e32 v19, v24, v24
	v_mul_f32_e32 v24, v20, v20
	v_max_f32_e32 v20, v25, v25
	v_max_f32_e32 v18, 0, v18
	v_max_f32_e32 v19, 0, v19
	v_max_f32_e32 v20, 0, v20
	v_max_f32_e32 v22, 0, v22
	v_mul_f32_e32 v18, v18, v18
	v_mul_f32_e32 v19, v19, v19
	v_max_f32_e32 v21, 0, v21
	v_mul_f32_e32 v20, v20, v20
	v_max_f32_e32 v10, v10, v10
	v_lshl_add_u64 v[34:35], v[146:147], 0, s[28:29]
	v_mul_f32_e32 v22, v22, v22
	v_mul_f32_e32 v21, v21, v21
	v_cvt_pk_bf16_f32 v18, v22, v18
	v_cvt_pk_bf16_f32 v19, v19, v20
	v_cvt_pk_bf16_f32 v20, v26, v23
	v_max_f32_e32 v10, 0, v10
	v_max_f32_e32 v11, v11, v11
	v_max_f32_e32 v12, v12, v12
	v_cvt_pk_bf16_f32 v21, v24, v21
	global_store_dwordx4 v[34:35], v[18:21], off offset:256 nt
	v_max_f32_e32 v14, v14, v14
	v_max_f32_e32 v11, 0, v11
	v_mul_f32_e32 v20, v10, v10
	v_max_f32_e32 v10, v15, v15
	v_max_f32_e32 v12, 0, v12
	v_max_f32_e32 v14, 0, v14
	v_max_f32_e32 v10, 0, v10
	v_mul_f32_e32 v15, v11, v11
	v_max_f32_e32 v11, v16, v16
	v_mul_f32_e32 v16, v12, v12
	v_max_f32_e32 v12, v17, v17
	v_mul_f32_e32 v14, v14, v14
	v_mul_f32_e32 v10, v10, v10
	v_max_f32_e32 v11, 0, v11
	v_max_f32_e32 v12, 0, v12
	v_max_f32_e32 v13, v13, v13
	v_mul_f32_e32 v11, v11, v11
	v_max_f32_e32 v13, 0, v13
	v_mul_f32_e32 v12, v12, v12
	v_cvt_pk_bf16_f32 v10, v14, v10
	v_add_co_u32_e32 v14, vcc, s67, v146
	v_max_f32_e32 v2, v2, v2
	v_max_f32_e32 v3, v3, v3
	v_max_f32_e32 v4, v4, v4
	v_mul_f32_e32 v13, v13, v13
	v_cvt_pk_bf16_f32 v11, v11, v12
	v_cvt_pk_bf16_f32 v12, v20, v15
	v_addc_co_u32_e32 v15, vcc, 0, v147, vcc
	v_max_f32_e32 v2, 0, v2
	v_max_f32_e32 v3, 0, v3
	v_max_f32_e32 v4, 0, v4
	v_cvt_pk_bf16_f32 v13, v16, v13
	global_store_dwordx4 v[14:15], v[10:13], off nt
	v_max_f32_e32 v5, v5, v5
	v_max_f32_e32 v6, v6, v6
	v_mul_f32_e32 v10, v2, v2
	v_max_f32_e32 v2, v7, v7
	v_mul_f32_e32 v7, v3, v3
	v_max_f32_e32 v3, v8, v8
	v_mul_f32_e32 v8, v4, v4
	v_max_f32_e32 v4, v9, v9
	v_max_f32_e32 v2, 0, v2
	v_max_f32_e32 v3, 0, v3
	v_max_f32_e32 v4, 0, v4
	v_max_f32_e32 v5, 0, v5
	v_lshl_add_u64 v[18:19], v[146:147], 0, s[30:31]
	v_max_f32_e32 v6, 0, v6
	v_mul_f32_e32 v2, v2, v2
	v_mul_f32_e32 v3, v3, v3
	v_mul_f32_e32 v4, v4, v4
	v_mul_f32_e32 v5, v5, v5
	s_andn2_b64 vcc, exec, s[6:7]
	s_mov_b64 s[6:7], -1
	v_mul_f32_e32 v6, v6, v6
	v_cvt_pk_bf16_f32 v2, v6, v2
	v_cvt_pk_bf16_f32 v3, v3, v4
	v_cvt_pk_bf16_f32 v4, v10, v7
	v_cvt_pk_bf16_f32 v5, v8, v5
	global_store_dwordx4 v[18:19], v[2:5], off offset:256 nt
	s_cbranch_vccnz .LBB0_2710
	s_andn2_b64 vcc, exec, s[14:15]
	s_cbranch_vccnz .LBB0_2709
	s_barrier
	s_branch .LBB0_2709
